# v87 + gate-phase output stores widened the same way (permlane16_swap, 2x dwordx2 -> 1x dwordx4 per 16-row group)
# speedup vs baseline: 1.0016x; 1.0016x over previous
.LBB0_155:
	s_or_b64 exec, exec, s[28:29]
	ds_write_b128 v158, v[12:15] offset:36864
	ds_write_b128 v159, v[16:19] offset:36864
	ds_write_b128 v160, v[28:31] offset:36864
	ds_write_b128 v161, v[32:35] offset:36864
	ds_write_b128 v162, v[44:47] offset:36864
	ds_write_b128 v163, v[48:51] offset:36864
	ds_write_b128 v164, v[60:63] offset:36864
	ds_write_b128 v165, v[64:67] offset:36864
	s_waitcnt lgkmcnt(0)
	s_barrier
	ds_read_b128 v[12:15], v148
	s_mov_b32 s22, 0x5040100
	s_waitcnt lgkmcnt(0)
	v_mul_f32_e32 v12, v68, v12
	v_mul_f32_e32 v13, v69, v13
	v_cndmask_b32_e64 v12, v12, 0, s[62:63]
	v_cndmask_b32_e64 v13, 0, v13, s[64:65]
	v_mul_f32_e32 v14, v70, v14
	v_mul_f32_e32 v15, v71, v15
	v_cndmask_b32_e64 v14, v14, 0, s[66:67]
	v_cndmask_b32_e64 v15, v15, 0, s[2:3]
	v_cvt_pk_bf16_f32 v12, v12, v13
	v_cvt_pk_bf16_f32 v13, v14, v15
	ds_write_b64 v166, v[12:13] offset:1024
	ds_read_b128 v[12:15], v148
	s_waitcnt lgkmcnt(0)
	v_mul_f32_e32 v12, v52, v12
	v_mul_f32_e32 v13, v53, v13
	v_cndmask_b32_e64 v12, v12, 0, s[70:71]
	v_cndmask_b32_e64 v13, 0, v13, s[72:73]
	v_mul_f32_e32 v14, v54, v14
	v_mul_f32_e32 v15, v55, v15
	v_cndmask_b32_e64 v14, v14, 0, s[74:75]
	v_cndmask_b32_e64 v15, v15, 0, s[76:77]
	v_cvt_pk_bf16_f32 v12, v12, v13
	v_cvt_pk_bf16_f32 v13, v14, v15
	ds_write_b64 v167, v[12:13] offset:1024
	ds_read_b128 v[12:15], v148
	s_waitcnt lgkmcnt(0)
	v_mul_f32_e32 v12, v56, v12
	v_mul_f32_e32 v13, v57, v13
	v_cndmask_b32_e64 v12, v12, 0, s[78:79]
	v_cndmask_b32_e64 v13, 0, v13, s[80:81]
	v_mul_f32_e32 v14, v58, v14
	v_mul_f32_e32 v15, v59, v15
	v_cndmask_b32_e64 v14, v14, 0, s[82:83]
	v_cndmask_b32_e64 v15, v15, 0, s[84:85]
	v_cvt_pk_bf16_f32 v12, v12, v13
	v_cvt_pk_bf16_f32 v13, v14, v15
	ds_write_b64 v168, v[12:13] offset:1024
	ds_read_b128 v[12:15], v148
	s_waitcnt lgkmcnt(0)
	v_mul_f32_e32 v12, v36, v12
	v_mul_f32_e32 v13, v37, v13
	v_cndmask_b32_e64 v12, v12, 0, s[86:87]
	v_cndmask_b32_e64 v13, 0, v13, s[88:89]
	v_mul_f32_e32 v14, v38, v14
	v_mul_f32_e32 v15, v39, v15
	v_cndmask_b32_e64 v14, v14, 0, s[90:91]
	v_cndmask_b32_e64 v15, v15, 0, s[92:93]
	v_cvt_pk_bf16_f32 v12, v12, v13
	v_cvt_pk_bf16_f32 v13, v14, v15
	ds_write_b64 v169, v[12:13] offset:1024
	ds_read_b128 v[12:15], v148
	s_waitcnt lgkmcnt(0)
	v_mul_f32_e32 v12, v40, v12
	v_mul_f32_e32 v13, v41, v13
	v_cndmask_b32_e64 v12, v12, 0, s[94:95]
	v_cndmask_b32_e64 v13, 0, v13, s[96:97]
	v_mul_f32_e32 v14, v42, v14
	v_mul_f32_e32 v15, v43, v15
	v_cndmask_b32_e64 v14, v14, 0, s[38:39]
	v_cndmask_b32_e64 v15, v15, 0, s[40:41]
	v_cvt_pk_bf16_f32 v12, v12, v13
	v_cvt_pk_bf16_f32 v13, v14, v15
	ds_write_b64 v170, v[12:13] offset:1024
	ds_read_b128 v[12:15], v148
	s_waitcnt lgkmcnt(0)
	v_mul_f32_e32 v12, v20, v12
	v_mul_f32_e32 v13, v21, v13
	v_cndmask_b32_e64 v12, v12, 0, s[42:43]
	v_cndmask_b32_e64 v13, 0, v13, s[44:45]
	v_mul_f32_e32 v14, v22, v14
	v_mul_f32_e32 v15, v23, v15
	v_cndmask_b32_e64 v14, v14, 0, s[46:47]
	v_cndmask_b32_e64 v15, v15, 0, s[48:49]
	v_cvt_pk_bf16_f32 v12, v12, v13
	v_cvt_pk_bf16_f32 v13, v14, v15
	ds_write_b64 v171, v[12:13] offset:1024
	ds_read_b128 v[12:15], v148
	s_waitcnt lgkmcnt(0)
	v_mul_f32_e32 v12, v24, v12
	v_mul_f32_e32 v13, v25, v13
	v_cndmask_b32_e64 v12, v12, 0, s[50:51]
	v_cndmask_b32_e64 v13, 0, v13, s[52:53]
	v_mul_f32_e32 v14, v26, v14
	v_mul_f32_e32 v15, v27, v15
	v_cndmask_b32_e64 v14, v14, 0, s[54:55]
	v_cndmask_b32_e64 v15, v15, 0, s[56:57]
	v_cvt_pk_bf16_f32 v12, v12, v13
	v_cvt_pk_bf16_f32 v13, v14, v15
	ds_write_b64 v172, v[12:13] offset:1024
	ds_read_b128 v[12:15], v148
	s_waitcnt lgkmcnt(0)
	v_mul_f32_e32 v8, v8, v12
	v_mul_f32_e32 v9, v9, v13
	v_cndmask_b32_e64 v8, v8, 0, s[4:5]
	v_cndmask_b32_e64 v9, 0, v9, s[6:7]
	v_mul_f32_e32 v10, v10, v14
	v_mul_f32_e32 v11, v11, v15
	v_cndmask_b32_e64 v10, v10, 0, s[8:9]
	v_cndmask_b32_e64 v11, v11, 0, s[10:11]
	v_cvt_pk_bf16_f32 v8, v8, v9
	v_cvt_pk_bf16_f32 v9, v10, v11
	ds_write_b64 v173, v[8:9] offset:1024
	s_waitcnt lgkmcnt(0)
	s_barrier
	ds_read_u16 v8, v174 offset:37392
	ds_read_u16 v9, v174 offset:37920
	ds_read_u16 v10, v174 offset:38448
	ds_read_u16 v11, v174 offset:38976
	ds_read_u16 v12, v174 offset:39504
	ds_read_u16 v13, v174 offset:40032
	ds_read_u16 v14, v174 offset:40560
	ds_read_u16 v15, v174 offset:36864
	ds_read_u16 v16, v174 offset:36896
	ds_read_u16 v17, v174 offset:37424
	ds_read_u16 v18, v174 offset:37952
	ds_read_u16 v19, v174 offset:38480
	ds_read_u16 v20, v174 offset:39008
	ds_read_u16 v21, v174 offset:39536
	ds_read_u16 v22, v174 offset:40064
	ds_read_u16 v23, v174 offset:40592
	s_waitcnt lgkmcnt(9)
	v_perm_b32 v27, v14, v13, s22
	v_perm_b32 v26, v12, v11, s22
	v_perm_b32 v25, v10, v9, s22
	s_waitcnt lgkmcnt(8)
	v_perm_b32 v24, v8, v15, s22
	s_waitcnt lgkmcnt(0)
	v_perm_b32 v31, v23, v22, s22
	v_perm_b32 v30, v21, v20, s22
	v_perm_b32 v29, v19, v18, s22
	v_perm_b32 v28, v17, v16, s22
	ds_read_b128 v[32:35], v175 offset:9728
	s_waitcnt lgkmcnt(0)
	v_mfma_f32_16x16x32_bf16 v[36:39], v[24:27], v[32:35], 0
	ds_read_b128 v[8:11], v175 offset:1024
	ds_read_b128 v[12:15], v175 offset:5376
	v_mfma_f32_16x16x32_bf16 v[40:43], v[28:31], v[32:35], 0
	ds_read_b128 v[32:35], v175 offset:14080
	s_waitcnt lgkmcnt(0)
	v_mfma_f32_16x16x32_bf16 v[44:47], v[24:27], v[32:35], 0
	v_mfma_f32_16x16x32_bf16 v[48:51], v[28:31], v[32:35], 0
	ds_read_b128 v[32:35], v175 offset:18432
	s_waitcnt lgkmcnt(0)
	v_mfma_f32_16x16x32_bf16 v[52:55], v[24:27], v[32:35], 0
	v_mfma_f32_16x16x32_bf16 v[56:59], v[28:31], v[32:35], 0
	ds_read_b128 v[32:35], v175 offset:22784
	s_waitcnt lgkmcnt(0)
	v_mfma_f32_16x16x32_bf16 v[60:63], v[24:27], v[32:35], 0
	v_mfma_f32_16x16x32_bf16 v[64:67], v[28:31], v[32:35], 0
	ds_read_b128 v[32:35], v175 offset:27136
	s_waitcnt lgkmcnt(0)
	v_mfma_f32_16x16x32_bf16 v[68:71], v[24:27], v[32:35], 0
	v_mfma_f32_16x16x32_bf16 v[72:75], v[28:31], v[32:35], 0
	ds_read_b128 v[32:35], v175 offset:31488
	v_mfma_f32_16x16x32_bf16 v[16:19], v[24:27], v[8:11], 0
	v_mfma_f32_16x16x32_bf16 v[8:11], v[28:31], v[8:11], 0
	v_mfma_f32_16x16x32_bf16 v[20:23], v[24:27], v[12:15], 0
	s_nop 5
	v_fma_f32 v16, v4, v16, v198
	v_fma_f32 v17, v5, v17, v198
	v_fma_f32 v8, v0, v8, v198
	v_mfma_f32_16x16x32_bf16 v[12:15], v[28:31], v[12:15], 0
	s_waitcnt lgkmcnt(0)
	v_mfma_f32_16x16x32_bf16 v[76:79], v[24:27], v[32:35], 0
	v_fma_f32 v20, v4, v20, v197
	v_mfma_f32_16x16x32_bf16 v[80:83], v[28:31], v[32:35], 0
	ds_read_u16 v24, v174 offset:53760
	ds_read_u16 v25, v174 offset:54288
	ds_read_u16 v26, v174 offset:54816
	ds_read_u16 v27, v174 offset:55344
	ds_read_u16 v28, v174 offset:55872
	ds_read_u16 v29, v174 offset:56400
	ds_read_u16 v30, v174 offset:56928
	ds_read_u16 v31, v174 offset:57456
	ds_read_u16 v32, v174 offset:53792
	ds_read_u16 v33, v174 offset:54320
	ds_read_u16 v34, v174 offset:54848
	ds_read_u16 v35, v174 offset:55376
	ds_read_u16 v199, v174 offset:55904
	ds_read_u16 v204, v174 offset:56432
	ds_read_u16 v214, v174 offset:56960
	ds_read_u16 v215, v174 offset:57488
	s_waitcnt lgkmcnt(8)
	v_perm_b32 v213, v31, v30, s22
	v_perm_b32 v212, v29, v28, s22
	v_perm_b32 v211, v27, v26, s22
	v_perm_b32 v210, v25, v24, s22
	s_waitcnt lgkmcnt(0)
	v_perm_b32 v217, v215, v214, s22
	v_perm_b32 v216, v204, v199, s22
	v_perm_b32 v215, v35, v34, s22
	v_perm_b32 v214, v33, v32, s22
	ds_read_b128 v[24:27], v175 offset:9792
	ds_read_b128 v[28:31], v175 offset:14144
	s_waitcnt lgkmcnt(1)
	v_mfma_f32_16x16x32_bf16 v[32:35], v[210:213], v[24:27], v[36:39]
	v_mfma_f32_16x16x32_bf16 v[24:27], v[214:217], v[24:27], v[40:43]
	s_nop 2
	ds_read_b128 v[40:43], v175 offset:18496
	s_waitcnt lgkmcnt(1)
	v_mfma_f32_16x16x32_bf16 v[36:39], v[210:213], v[28:31], v[44:47]
	s_waitcnt lgkmcnt(0)
	v_mfma_f32_16x16x32_bf16 v[44:47], v[210:213], v[40:43], v[52:55]
	s_nop 2
	ds_read_b128 v[52:55], v175 offset:22848
	v_mfma_f32_16x16x32_bf16 v[28:31], v[214:217], v[28:31], v[48:51]
	s_waitcnt lgkmcnt(0)
	v_mfma_f32_16x16x32_bf16 v[48:51], v[210:213], v[52:55], v[60:63]
	s_nop 2
	ds_read_b128 v[60:63], v175 offset:27200
	v_mfma_f32_16x16x32_bf16 v[40:43], v[214:217], v[40:43], v[56:59]
	s_waitcnt lgkmcnt(0)
	v_mfma_f32_16x16x32_bf16 v[56:59], v[210:213], v[60:63], v[68:71]
	s_nop 2
	ds_read_b128 v[68:71], v175 offset:31552
	v_mfma_f32_16x16x32_bf16 v[52:55], v[214:217], v[52:55], v[64:67]
	v_mfma_f32_16x16x32_bf16 v[60:63], v[214:217], v[60:63], v[72:75]
	s_waitcnt lgkmcnt(0)
	v_mfma_f32_16x16x32_bf16 v[64:67], v[210:213], v[68:71], v[76:79]
	v_mfma_f32_16x16x32_bf16 v[68:71], v[214:217], v[68:71], v[80:83]
	ds_read_u16 v72, v176 offset:36864
	s_nop 0
	ds_read_u16 v76, v176 offset:36896
	ds_read_u16 v77, v177 offset:36864
	ds_read_u16 v80, v177 offset:36896
	ds_read_u16 v73, v178 offset:36864
	ds_read_u16 v81, v178 offset:36896
	ds_read_u16 v78, v179 offset:36864
	ds_read_u16 v82, v179 offset:36896
	ds_read_u16 v74, v180 offset:36864
	ds_read_u16 v83, v180 offset:36896
	ds_read_u16 v79, v181 offset:36864
	ds_read_u16 v199, v181 offset:36896
	ds_read_u16 v75, v182 offset:36864
	ds_read_u16 v204, v182 offset:36896
	ds_read_u16 v210, v183 offset:36864
	ds_read_u16 v211, v183 offset:36896
	s_waitcnt lgkmcnt(5)
	v_perm_b32 v74, v79, v74, s22
	v_perm_b32 v73, v78, v73, s22
	v_perm_b32 v72, v77, v72, s22
	s_waitcnt lgkmcnt(1)
	v_perm_b32 v75, v210, v75, s22
	s_waitcnt lgkmcnt(0)
	v_perm_b32 v79, v211, v204, s22
	v_perm_b32 v78, v199, v83, s22
	v_perm_b32 v77, v82, v81, s22
	v_perm_b32 v76, v80, v76, s22
	ds_read_b128 v[80:83], v175 offset:18560
	ds_read_b128 v[210:213], v175 offset:22912
	s_waitcnt lgkmcnt(1)
	v_mfma_f32_16x16x32_bf16 v[44:47], v[72:75], v[80:83], v[44:47]
	v_mfma_f32_16x16x32_bf16 v[40:43], v[76:79], v[80:83], v[40:43]
	s_waitcnt lgkmcnt(0)
	v_mfma_f32_16x16x32_bf16 v[80:83], v[72:75], v[210:213], v[48:51]
	v_mfma_f32_16x16x32_bf16 v[48:51], v[76:79], v[210:213], v[52:55]
	s_nop 2
	ds_read_b128 v[52:55], v175 offset:27264
	s_waitcnt lgkmcnt(0)
	v_mfma_f32_16x16x32_bf16 v[56:59], v[72:75], v[52:55], v[56:59]
	v_mfma_f32_16x16x32_bf16 v[52:55], v[76:79], v[52:55], v[60:63]
	s_nop 2
	ds_read_b128 v[60:63], v175 offset:31616
	s_waitcnt lgkmcnt(0)
	v_mfma_f32_16x16x32_bf16 v[64:67], v[72:75], v[60:63], v[64:67]
	v_mfma_f32_16x16x32_bf16 v[60:63], v[76:79], v[60:63], v[68:71]
	s_nop 2
	ds_read_u16 v68, v184 offset:36864
	ds_read_u16 v72, v184 offset:36896
	ds_read_u16 v73, v185 offset:36864
	ds_read_u16 v76, v185 offset:36896
	ds_read_u16 v69, v186 offset:36864
	ds_read_u16 v77, v186 offset:36896
	ds_read_u16 v74, v187 offset:36864
	ds_read_u16 v78, v187 offset:36896
	ds_read_u16 v70, v188 offset:36864
	ds_read_u16 v79, v188 offset:36896
	ds_read_u16 v75, v189 offset:36864
	ds_read_u16 v199, v189 offset:36896
	ds_read_u16 v71, v190 offset:36864
	ds_read_u16 v204, v190 offset:36896
	ds_read_u16 v210, v191 offset:36864
	ds_read_u16 v211, v191 offset:36896
	s_waitcnt lgkmcnt(5)
	v_perm_b32 v70, v75, v70, s22
	v_perm_b32 v69, v74, v69, s22
	v_perm_b32 v68, v73, v68, s22
	s_waitcnt lgkmcnt(1)
	v_perm_b32 v71, v210, v71, s22
	v_perm_b32 v74, v199, v79, s22
	v_perm_b32 v73, v78, v77, s22
	v_perm_b32 v72, v76, v72, s22
	ds_read_b128 v[76:79], v175 offset:27328
	s_waitcnt lgkmcnt(1)
	v_perm_b32 v75, v211, v204, s22
	s_waitcnt lgkmcnt(0)
	v_mfma_f32_16x16x32_bf16 v[210:213], v[68:71], v[76:79], v[56:59]
	s_nop 2
	ds_read_b128 v[56:59], v175 offset:31680
	v_readlane_b32 s22, v254, 34
	s_add_i32 s21, s21, s22
	s_waitcnt lgkmcnt(0)
	v_mfma_f32_16x16x32_bf16 v[64:67], v[68:71], v[56:59], v[64:67]
	v_lshlrev_b32_e32 v68, 16, v141
	v_and_b32_e32 v69, 0xffff0000, v141
	s_cmpk_lt_i32 s21, 0x200
	v_mfma_f32_16x16x32_bf16 v[56:59], v[72:75], v[56:59], v[60:63]
	v_readlane_b32 s22, v252, 9
	s_cselect_b64 s[28:29], -1, 0
	s_cmp_lt_u32 s25, s22
	v_lshlrev_b32_e32 v62, 16, v140
	v_and_b32_e32 v63, 0xffff0000, v140
	v_mul_f32_e32 v16, v16, v62
	v_mul_f32_e32 v17, v17, v63
	v_cvt_pk_bf16_f32 v16, v16, v17
	v_fma_f32 v17, v6, v18, v198
	v_fma_f32 v18, v7, v19, v198
	v_lshl_add_u64 v[60:61], v[136:137], 1, s[34:35]
	v_mul_f32_e32 v17, v17, v68
	v_mul_f32_e32 v18, v18, v69
	v_cvt_pk_bf16_f32 v17, v17, v18
	v_lshl_add_u64 v[18:19], v[60:61], 0, v[108:109]
	v_bfe_u32 v255, v234, 4, 1
	v_mul_u32_u24_e32 v255, 24, v255
	v_mov_b32_e32 v218, v16
	v_mov_b32_e32 v219, v17
	v_lshlrev_b32_e32 v16, 16, v138
	v_and_b32_e32 v17, 0xffff0000, v138
	v_mul_f32_e32 v16, v20, v16
	v_fma_f32 v20, v5, v21, v197
	v_mul_f32_e32 v17, v20, v17
	v_lshlrev_b32_e32 v18, 16, v139
	v_cvt_pk_bf16_f32 v16, v16, v17
	v_fma_f32 v17, v6, v22, v197
	v_and_b32_e32 v19, 0xffff0000, v139
	v_mul_f32_e32 v17, v17, v18
	v_fma_f32 v18, v7, v23, v197
	v_mul_f32_e32 v18, v18, v19
	v_cvt_pk_bf16_f32 v17, v17, v18
	v_lshl_add_u64 v[18:19], v[60:61], 0, v[104:105]
	v_mov_b32_e32 v220, v16
	v_mov_b32_e32 v221, v17
	v_lshlrev_b32_e32 v16, 16, v134
	v_fma_f32 v20, v4, v32, v196
	v_and_b32_e32 v17, 0xffff0000, v134
	v_mul_f32_e32 v16, v20, v16
	v_fma_f32 v20, v5, v33, v196
	v_mul_f32_e32 v17, v20, v17
	v_lshlrev_b32_e32 v18, 16, v135
	v_cvt_pk_bf16_f32 v16, v16, v17
	v_fma_f32 v17, v6, v34, v196
	v_and_b32_e32 v19, 0xffff0000, v135
	v_mul_f32_e32 v17, v17, v18
	v_fma_f32 v18, v7, v35, v196
	v_mul_f32_e32 v18, v18, v19
	v_cvt_pk_bf16_f32 v17, v17, v18
	v_lshl_add_u64 v[18:19], v[60:61], 0, v[102:103]
	v_mov_b32_e32 v222, v16
	v_mov_b32_e32 v223, v17
	v_lshlrev_b32_e32 v16, 16, v130
	v_fma_f32 v20, v4, v36, v195
	v_and_b32_e32 v17, 0xffff0000, v130
	v_mul_f32_e32 v16, v20, v16
	v_fma_f32 v20, v5, v37, v195
	v_mul_f32_e32 v17, v20, v17
	v_lshlrev_b32_e32 v18, 16, v131
	v_cvt_pk_bf16_f32 v16, v16, v17
	v_fma_f32 v17, v6, v38, v195
	v_and_b32_e32 v19, 0xffff0000, v131
	v_mul_f32_e32 v17, v17, v18
	v_fma_f32 v18, v7, v39, v195
	v_mul_f32_e32 v18, v18, v19
	v_cvt_pk_bf16_f32 v17, v17, v18
	v_lshl_add_u64 v[18:19], v[60:61], 0, v[98:99]
	v_mov_b32_e32 v224, v16
	v_mov_b32_e32 v225, v17
	v_lshlrev_b32_e32 v16, 16, v132
	v_fma_f32 v20, v4, v44, v194
	v_and_b32_e32 v17, 0xffff0000, v132
	v_mul_f32_e32 v16, v20, v16
	v_fma_f32 v20, v5, v45, v194
	v_mul_f32_e32 v17, v20, v17
	v_lshlrev_b32_e32 v18, 16, v133
	v_cvt_pk_bf16_f32 v16, v16, v17
	v_fma_f32 v17, v6, v46, v194
	v_and_b32_e32 v19, 0xffff0000, v133
	v_mul_f32_e32 v17, v17, v18
	v_fma_f32 v18, v7, v47, v194
	v_mul_f32_e32 v18, v18, v19
	v_cvt_pk_bf16_f32 v17, v17, v18
	v_lshl_add_u64 v[18:19], v[60:61], 0, v[96:97]
	v_mov_b32_e32 v226, v16
	v_mov_b32_e32 v227, v17
	v_lshlrev_b32_e32 v16, 16, v128
	v_fma_f32 v20, v4, v80, v193
	v_and_b32_e32 v17, 0xffff0000, v128
	v_mul_f32_e32 v16, v20, v16
	v_fma_f32 v20, v5, v81, v193
	v_mul_f32_e32 v17, v20, v17
	v_lshlrev_b32_e32 v18, 16, v129
	v_cvt_pk_bf16_f32 v16, v16, v17
	v_fma_f32 v17, v6, v82, v193
	v_and_b32_e32 v19, 0xffff0000, v129
	v_mul_f32_e32 v17, v17, v18
	v_fma_f32 v18, v7, v83, v193
	v_mul_f32_e32 v18, v18, v19
	v_cvt_pk_bf16_f32 v17, v17, v18
	v_lshl_add_u64 v[18:19], v[60:61], 0, v[94:95]
	v_mov_b32_e32 v228, v16
	v_mov_b32_e32 v229, v17
	v_lshlrev_b32_e32 v16, 16, v126
	v_fma_f32 v20, v4, v210, v192
	v_and_b32_e32 v17, 0xffff0000, v126
	v_mul_f32_e32 v16, v20, v16
	v_fma_f32 v20, v5, v211, v192
	v_mul_f32_e32 v17, v20, v17
	v_lshlrev_b32_e32 v18, 16, v127
	v_cvt_pk_bf16_f32 v16, v16, v17
	v_fma_f32 v17, v6, v212, v192
	v_and_b32_e32 v19, 0xffff0000, v127
	v_mul_f32_e32 v17, v17, v18
	v_fma_f32 v18, v7, v213, v192
	v_mul_f32_e32 v18, v18, v19
	v_cvt_pk_bf16_f32 v17, v17, v18
	v_lshl_add_u64 v[18:19], v[60:61], 0, v[92:93]
	v_mov_b32_e32 v230, v16
	v_mov_b32_e32 v231, v17
	v_lshlrev_b32_e32 v16, 16, v124
	v_and_b32_e32 v17, 0xffff0000, v124
	v_fma_f32 v4, v4, v64, v113
	v_fma_f32 v5, v5, v65, v113
	v_mul_f32_e32 v4, v4, v16
	v_mul_f32_e32 v5, v5, v17
	v_lshlrev_b32_e32 v18, 16, v125
	v_and_b32_e32 v19, 0xffff0000, v125
	v_cvt_pk_bf16_f32 v4, v4, v5
	v_fma_f32 v5, v6, v66, v113
	v_fma_f32 v6, v7, v67, v113
	v_mul_f32_e32 v5, v5, v18
	v_mul_f32_e32 v6, v6, v19
	v_cvt_pk_bf16_f32 v5, v5, v6
	v_or_b32_e32 v6, 0x70, v112
	v_ashrrev_i32_e32 v7, 31, v6
	v_lshlrev_b64 v[6:7], 12, v[6:7]
	v_lshl_add_u64 v[16:17], v[60:61], 0, v[6:7]
	v_mov_b32_e32 v232, v4
	v_mov_b32_e32 v233, v5
	v_lshlrev_b32_e32 v4, 16, v122
	v_and_b32_e32 v5, 0xffff0000, v122
	v_mul_f32_e32 v4, v8, v4
	v_fma_f32 v8, v1, v9, v198
	v_mul_f32_e32 v5, v8, v5
	v_lshlrev_b32_e32 v16, 16, v123
	v_and_b32_e32 v17, 0xffff0000, v123
	v_cvt_pk_bf16_f32 v4, v4, v5
	v_fma_f32 v5, v2, v10, v198
	v_fmac_f32_e32 v198, v3, v11
	v_mul_f32_e32 v5, v5, v16
	v_mul_f32_e32 v8, v198, v17
	v_cvt_pk_bf16_f32 v5, v5, v8
	v_lshl_add_u64 v[8:9], s[34:35], 0, v[108:109]
	v_lshl_add_u64 v[8:9], v[8:9], 0, v[90:91]
	v_mov_b32_e32 v214, v218
	v_mov_b32_e32 v215, v219
	v_mov_b32_e32 v216, v4
	v_mov_b32_e32 v217, v5
	v_add_u32_e32 v8, v8, v255
	s_nop 1
	v_permlane16_swap_b32_e32 v214, v216
	v_permlane16_swap_b32_e32 v215, v217
	global_store_dwordx4 v[8:9], v[214:217], off offset:-32
	v_lshlrev_b32_e32 v4, 16, v120
	v_fma_f32 v10, v0, v12, v197
	v_and_b32_e32 v5, 0xffff0000, v120
	v_mul_f32_e32 v4, v10, v4
	v_fma_f32 v10, v1, v13, v197
	v_mul_f32_e32 v5, v10, v5
	v_lshlrev_b32_e32 v8, 16, v121
	v_and_b32_e32 v9, 0xffff0000, v121
	v_cvt_pk_bf16_f32 v4, v4, v5
	v_fma_f32 v5, v2, v14, v197
	v_fmac_f32_e32 v197, v3, v15
	v_mul_f32_e32 v5, v5, v8
	v_mul_f32_e32 v8, v197, v9
	v_cvt_pk_bf16_f32 v5, v5, v8
	v_lshl_add_u64 v[8:9], s[34:35], 0, v[104:105]
	v_lshl_add_u64 v[8:9], v[8:9], 0, v[90:91]
	v_mov_b32_e32 v214, v220
	v_mov_b32_e32 v215, v221
	v_mov_b32_e32 v216, v4
	v_mov_b32_e32 v217, v5
	v_add_u32_e32 v8, v8, v255
	s_nop 1
	v_permlane16_swap_b32_e32 v214, v216
	v_permlane16_swap_b32_e32 v215, v217
	global_store_dwordx4 v[8:9], v[214:217], off offset:-32
	v_lshlrev_b32_e32 v4, 16, v118
	v_fma_f32 v10, v0, v24, v196
	v_and_b32_e32 v5, 0xffff0000, v118
	v_mul_f32_e32 v4, v10, v4
	v_fma_f32 v10, v1, v25, v196
	v_mul_f32_e32 v5, v10, v5
	v_lshlrev_b32_e32 v8, 16, v119
	v_and_b32_e32 v9, 0xffff0000, v119
	v_cvt_pk_bf16_f32 v4, v4, v5
	v_fma_f32 v5, v2, v26, v196
	v_fmac_f32_e32 v196, v3, v27
	v_mul_f32_e32 v5, v5, v8
	v_mul_f32_e32 v8, v196, v9
	v_cvt_pk_bf16_f32 v5, v5, v8
	v_lshl_add_u64 v[8:9], s[34:35], 0, v[102:103]
	v_lshl_add_u64 v[8:9], v[8:9], 0, v[90:91]
	v_mov_b32_e32 v214, v222
	v_mov_b32_e32 v215, v223
	v_mov_b32_e32 v216, v4
	v_mov_b32_e32 v217, v5
	v_add_u32_e32 v8, v8, v255
	s_nop 1
	v_permlane16_swap_b32_e32 v214, v216
	v_permlane16_swap_b32_e32 v215, v217
	global_store_dwordx4 v[8:9], v[214:217], off offset:-32
	v_lshlrev_b32_e32 v4, 16, v116
	v_fma_f32 v10, v0, v28, v195
	v_and_b32_e32 v5, 0xffff0000, v116
	v_mul_f32_e32 v4, v10, v4
	v_fma_f32 v10, v1, v29, v195
	v_mul_f32_e32 v5, v10, v5
	v_lshlrev_b32_e32 v8, 16, v117
	v_and_b32_e32 v9, 0xffff0000, v117
	v_cvt_pk_bf16_f32 v4, v4, v5
	v_fma_f32 v5, v2, v30, v195
	v_fmac_f32_e32 v195, v3, v31
	v_mul_f32_e32 v5, v5, v8
	v_mul_f32_e32 v8, v195, v9
	v_cvt_pk_bf16_f32 v5, v5, v8
	v_lshl_add_u64 v[8:9], s[34:35], 0, v[98:99]
	v_lshl_add_u64 v[8:9], v[8:9], 0, v[90:91]
	v_mov_b32_e32 v214, v224
	v_mov_b32_e32 v215, v225
	v_mov_b32_e32 v216, v4
	v_mov_b32_e32 v217, v5
	v_add_u32_e32 v8, v8, v255
	s_nop 1
	v_permlane16_swap_b32_e32 v214, v216
	v_permlane16_swap_b32_e32 v215, v217
	global_store_dwordx4 v[8:9], v[214:217], off offset:-32
	v_lshlrev_b32_e32 v4, 16, v114
	v_fma_f32 v10, v0, v40, v194
	v_and_b32_e32 v5, 0xffff0000, v114
	v_mul_f32_e32 v4, v10, v4
	v_fma_f32 v10, v1, v41, v194
	v_mul_f32_e32 v5, v10, v5
	v_lshlrev_b32_e32 v8, 16, v115
	v_and_b32_e32 v9, 0xffff0000, v115
	v_cvt_pk_bf16_f32 v4, v4, v5
	v_fma_f32 v5, v2, v42, v194
	v_fmac_f32_e32 v194, v3, v43
	v_mul_f32_e32 v5, v5, v8
	v_mul_f32_e32 v8, v194, v9
	v_cvt_pk_bf16_f32 v5, v5, v8
	v_lshl_add_u64 v[8:9], s[34:35], 0, v[96:97]
	v_lshl_add_u64 v[8:9], v[8:9], 0, v[90:91]
	v_mov_b32_e32 v214, v226
	v_mov_b32_e32 v215, v227
	v_mov_b32_e32 v216, v4
	v_mov_b32_e32 v217, v5
	v_add_u32_e32 v8, v8, v255
	s_nop 1
	v_permlane16_swap_b32_e32 v214, v216
	v_permlane16_swap_b32_e32 v215, v217
	global_store_dwordx4 v[8:9], v[214:217], off offset:-32
	v_lshlrev_b32_e32 v4, 16, v110
	v_fma_f32 v10, v0, v48, v193
	v_and_b32_e32 v5, 0xffff0000, v110
	v_mul_f32_e32 v4, v10, v4
	v_fma_f32 v10, v1, v49, v193
	v_mul_f32_e32 v5, v10, v5
	v_mfma_f32_16x16x32_bf16 v[52:55], v[72:75], v[76:79], v[52:55]
	v_lshlrev_b32_e32 v8, 16, v111
	v_and_b32_e32 v9, 0xffff0000, v111
	v_cvt_pk_bf16_f32 v4, v4, v5
	v_fma_f32 v5, v2, v50, v193
	v_fmac_f32_e32 v193, v3, v51
	v_mul_f32_e32 v5, v5, v8
	v_mul_f32_e32 v8, v193, v9
	v_cvt_pk_bf16_f32 v5, v5, v8
	v_lshl_add_u64 v[8:9], s[34:35], 0, v[94:95]
	v_lshl_add_u64 v[8:9], v[8:9], 0, v[90:91]
	v_mov_b32_e32 v214, v228
	v_mov_b32_e32 v215, v229
	v_mov_b32_e32 v216, v4
	v_mov_b32_e32 v217, v5
	v_add_u32_e32 v8, v8, v255
	s_nop 1
	v_permlane16_swap_b32_e32 v214, v216
	v_permlane16_swap_b32_e32 v215, v217
	global_store_dwordx4 v[8:9], v[214:217], off offset:-32
	v_lshlrev_b32_e32 v4, 16, v106
	v_fma_f32 v10, v0, v52, v192
	v_and_b32_e32 v5, 0xffff0000, v106
	v_mul_f32_e32 v4, v10, v4
	v_fma_f32 v10, v1, v53, v192
	v_mul_f32_e32 v5, v10, v5
	v_lshlrev_b32_e32 v8, 16, v107
	v_and_b32_e32 v9, 0xffff0000, v107
	v_cvt_pk_bf16_f32 v4, v4, v5
	v_fma_f32 v5, v2, v54, v192
	v_fmac_f32_e32 v192, v3, v55
	v_mul_f32_e32 v5, v5, v8
	v_mul_f32_e32 v8, v192, v9
	v_cvt_pk_bf16_f32 v5, v5, v8
	v_lshl_add_u64 v[8:9], s[34:35], 0, v[92:93]
	v_lshl_add_u64 v[8:9], v[8:9], 0, v[90:91]
	v_mov_b32_e32 v214, v230
	v_mov_b32_e32 v215, v231
	v_mov_b32_e32 v216, v4
	v_mov_b32_e32 v217, v5
	v_add_u32_e32 v8, v8, v255
	s_nop 1
	v_permlane16_swap_b32_e32 v214, v216
	v_permlane16_swap_b32_e32 v215, v217
	global_store_dwordx4 v[8:9], v[214:217], off offset:-32
	v_lshlrev_b32_e32 v4, 16, v100
	v_and_b32_e32 v5, 0xffff0000, v100
	v_fma_f32 v0, v0, v56, v113
	v_fma_f32 v1, v1, v57, v113
	v_mul_f32_e32 v0, v0, v4
	v_mul_f32_e32 v1, v1, v5
	v_lshlrev_b32_e32 v8, 16, v101
	v_and_b32_e32 v9, 0xffff0000, v101
	v_cvt_pk_bf16_f32 v0, v0, v1
	v_fma_f32 v1, v2, v58, v113
	v_fmac_f32_e32 v113, v3, v59
	v_mul_f32_e32 v1, v1, v8
	v_mul_f32_e32 v2, v113, v9
	s_cselect_b64 vcc, -1, 0
	v_cvt_pk_bf16_f32 v1, v1, v2
	v_lshl_add_u64 v[2:3], s[34:35], 0, v[6:7]
	s_and_b64 s[28:29], s[28:29], vcc
	v_readlane_b32 s22, v254, 35
	v_lshl_add_u64 v[2:3], v[2:3], 0, v[90:91]
	s_add_i32 s20, s20, s22
	s_add_i32 s25, s25, 1
	s_andn2_b64 vcc, exec, s[28:29]
	v_mov_b32_e32 v214, v232
	v_mov_b32_e32 v215, v233
	v_mov_b32_e32 v216, v0
	v_mov_b32_e32 v217, v1
	v_add_u32_e32 v2, v2, v255
	s_nop 1
	v_permlane16_swap_b32_e32 v214, v216
	v_permlane16_swap_b32_e32 v215, v217
	global_store_dwordx4 v[2:3], v[214:217], off offset:-32
	s_barrier
	s_cbranch_vccnz .LBB0_158

	.amdhsa_kernel _Z6mk_fwd4Args
		.amdhsa_group_segment_fixed_size 0
		.amdhsa_private_segment_fixed_size 0
		.amdhsa_kernarg_size 448
		.amdhsa_user_sgpr_count 2
		.amdhsa_user_sgpr_dispatch_ptr 0
		.amdhsa_user_sgpr_queue_ptr 0
		.amdhsa_user_sgpr_kernarg_segment_ptr 1
		.amdhsa_user_sgpr_dispatch_id 0
		.amdhsa_user_sgpr_kernarg_preload_length 0
		.amdhsa_user_sgpr_kernarg_preload_offset 0
		.amdhsa_user_sgpr_private_segment_size 0
		.amdhsa_uses_dynamic_stack 0
		.amdhsa_enable_private_segment 0
		.amdhsa_system_sgpr_workgroup_id_x 1
		.amdhsa_system_sgpr_workgroup_id_y 0
		.amdhsa_system_sgpr_workgroup_id_z 0
		.amdhsa_system_sgpr_workgroup_info 0
		.amdhsa_system_vgpr_workitem_id 2
		.amdhsa_next_free_vgpr 256
		.amdhsa_next_free_sgpr 100
		.amdhsa_accum_offset 256
		.amdhsa_reserve_vcc 1
		.amdhsa_float_round_mode_32 0
		.amdhsa_float_round_mode_16_64 0
		.amdhsa_float_denorm_mode_32 3
		.amdhsa_float_denorm_mode_16_64 3
		.amdhsa_dx10_clamp 1
		.amdhsa_ieee_mode 1
		.amdhsa_fp16_overflow 0
		.amdhsa_tg_split 0
		.amdhsa_exception_fp_ieee_invalid_op 0
		.amdhsa_exception_fp_denorm_src 0
		.amdhsa_exception_fp_ieee_div_zero 0
		.amdhsa_exception_fp_ieee_overflow 0
		.amdhsa_exception_fp_ieee_underflow 0
		.amdhsa_exception_fp_ieee_inexact 0
		.amdhsa_exception_int_div_zero 0
	.end_amdhsa_kernel

amdhsa.kernels:
  - .agpr_count:     0
    .args:
      - .offset:         0
        .size:           192
        .value_kind:     by_value
      - .offset:         192
        .size:           4
        .value_kind:     hidden_block_count_x
      - .offset:         196
        .size:           4
        .value_kind:     hidden_block_count_y
      - .offset:         200
        .size:           4
        .value_kind:     hidden_block_count_z
      - .offset:         204
        .size:           2
        .value_kind:     hidden_group_size_x
      - .offset:         206
        .size:           2
        .value_kind:     hidden_group_size_y
      - .offset:         208
        .size:           2
        .value_kind:     hidden_group_size_z
      - .offset:         210
        .size:           2
        .value_kind:     hidden_remainder_x
      - .offset:         212
        .size:           2
        .value_kind:     hidden_remainder_y
      - .offset:         214
        .size:           2
        .value_kind:     hidden_remainder_z
      - .offset:         232
        .size:           8
        .value_kind:     hidden_global_offset_x
      - .offset:         240
        .size:           8
        .value_kind:     hidden_global_offset_y
      - .offset:         248
        .size:           8
        .value_kind:     hidden_global_offset_z
      - .offset:         256
        .size:           2
        .value_kind:     hidden_grid_dims
      - .offset:         280
        .size:           8
        .value_kind:     hidden_multigrid_sync_arg
      - .offset:         312
        .size:           4
        .value_kind:     hidden_dynamic_lds_size
    .group_segment_fixed_size: 0
    .kernarg_segment_align: 8
    .kernarg_segment_size: 448
    .language:       OpenCL C
    .language_version:
      - 2
      - 0
    .max_flat_workgroup_size: 512
    .name:           _Z6mk_fwd4Args
    .private_segment_fixed_size: 0
    .sgpr_count:     106
    .sgpr_spill_count: 276
    .symbol:         _Z6mk_fwd4Args.kd
    .uniform_work_group_size: 1
    .uses_dynamic_stack: false
    .vgpr_count:     256
    .vgpr_spill_count: 0
    .wavefront_size: 64
